# v20 + route_a unit loop: both per-unit block barriers removed (the score rows in LDS are written and read by the same wave only)
# baseline (speedup 1.0000x reference)
.LBB0_949:
	s_and_b32 s18, s16, 0x7ff0
	s_and_b32 s0, s14, 4
	v_or_b32_e32 v0, s18, v137
	v_add_u32_e32 v41, s0, v129
	v_lshlrev_b32_e32 v0, 12, v0
	v_lshl_add_u64 v[42:43], s[70:71], 0, v[0:1]
	v_lshlrev_b32_e32 v0, 9, v41
	v_lshl_add_u64 v[42:43], v[42:43], 0, v[0:1]
	v_lshl_add_u64 v[42:43], v[42:43], 0, s[2:3]
	v_lshl_add_u64 v[54:55], v[42:43], 0, v[2:3]
	s_waitcnt vmcnt(8)
	v_mov_b32_e32 v42, v160
	v_mov_b32_e32 v43, v161
	v_mov_b32_e32 v44, v162
	v_mov_b32_e32 v45, v163
	v_mov_b32_e32 v46, v164
	v_mov_b32_e32 v47, v165
	v_mov_b32_e32 v48, v166
	v_mov_b32_e32 v49, v167
	v_mov_b32_e32 v50, v168
	v_mov_b32_e32 v51, v169
	v_mov_b32_e32 v52, v170
	v_mov_b32_e32 v53, v171
	v_mov_b32_e32 v54, v172
	v_mov_b32_e32 v55, v173
	v_mov_b32_e32 v56, v174
	v_mov_b32_e32 v57, v175
	s_add_i32 s20, s16, s17
	s_add_i32 s22, s14, s15
	s_and_b32 s23, s20, 0x7ff0
	s_and_b32 s24, s22, 4
	v_mov_b32_e32 v141, 0
	v_or_b32_e32 v140, s23, v137
	v_add_u32_e32 v178, s24, v129
	v_lshlrev_b32_e32 v140, 12, v140
	v_lshl_add_u64 v[176:177], s[70:71], 0, v[140:141]
	v_lshlrev_b32_e32 v140, 9, v178
	v_lshl_add_u64 v[176:177], v[176:177], 0, v[140:141]
	v_lshl_add_u64 v[176:177], v[176:177], 0, s[2:3]
	v_lshl_add_u64 v[176:177], v[176:177], 0, v[2:3]
	global_load_dwordx4 v[160:163], v[176:177], off
	global_load_dwordx4 v[164:167], v[176:177], off offset:64
	global_load_dwordx4 v[168:171], v[176:177], off offset:128
	global_load_dwordx4 v[172:175], v[176:177], off offset:192
	s_nop 0
	ds_read_b128 v[58:61], v6
	ds_read_b128 v[62:65], v6 offset:64
	ds_read_b128 v[66:69], v6 offset:4352
	ds_read_b128 v[84:87], v6 offset:4416
	ds_read_b128 v[88:91], v6 offset:8704
	ds_read_b128 v[92:95], v6 offset:8768
	ds_read_b128 v[96:99], v6 offset:13056
	ds_read_b128 v[100:103], v6 offset:13120
	ds_read_b128 v[104:107], v6 offset:17408
	ds_read_b128 v[108:111], v6 offset:17472
	ds_read_b128 v[112:115], v6 offset:21760
	ds_read_b128 v[116:119], v6 offset:21824
	ds_read_b128 v[120:123], v6 offset:26112
	ds_read_b128 v[124:127], v6 offset:26176
	s_waitcnt lgkmcnt(13)
	v_mfma_f32_16x16x32_bf16 v[58:61], v[42:45], v[58:61], 0
	s_waitcnt lgkmcnt(11)
	v_mfma_f32_16x16x32_bf16 v[66:69], v[42:45], v[66:69], 0
	s_waitcnt lgkmcnt(9)
	v_mfma_f32_16x16x32_bf16 v[88:91], v[42:45], v[88:91], 0
	s_waitcnt lgkmcnt(7)
	v_mfma_f32_16x16x32_bf16 v[96:99], v[42:45], v[96:99], 0
	s_waitcnt lgkmcnt(5)
	v_mfma_f32_16x16x32_bf16 v[104:107], v[42:45], v[104:107], 0
	v_mfma_f32_16x16x32_bf16 v[58:61], v[46:49], v[62:65], v[58:61]
	v_mfma_f32_16x16x32_bf16 v[62:65], v[46:49], v[84:87], v[66:69]
	v_mfma_f32_16x16x32_bf16 v[66:69], v[46:49], v[92:95], v[88:91]
	v_mfma_f32_16x16x32_bf16 v[84:87], v[46:49], v[100:103], v[96:99]
	s_waitcnt lgkmcnt(4)
	v_mfma_f32_16x16x32_bf16 v[88:91], v[46:49], v[108:111], v[104:107]
	ds_read_b128 v[100:103], v6 offset:128
	s_nop 1
	ds_read_b128 v[104:107], v6 offset:192
	s_waitcnt lgkmcnt(5)
	v_mfma_f32_16x16x32_bf16 v[112:115], v[42:45], v[112:115], 0
	s_waitcnt lgkmcnt(1)
	v_mfma_f32_16x16x32_bf16 v[58:61], v[50:53], v[100:103], v[58:61]
	ds_read_b128 v[100:103], v6 offset:4480
	ds_read_b128 v[108:111], v6 offset:4544
	v_mfma_f32_16x16x32_bf16 v[92:95], v[46:49], v[116:119], v[112:115]
	s_waitcnt lgkmcnt(1)
	v_mfma_f32_16x16x32_bf16 v[62:65], v[50:53], v[100:103], v[62:65]
	ds_read_b128 v[100:103], v6 offset:8832
	ds_read_b128 v[112:115], v6 offset:8896
	v_mfma_f32_16x16x32_bf16 v[120:123], v[42:45], v[120:123], 0
	s_waitcnt lgkmcnt(1)
	v_mfma_f32_16x16x32_bf16 v[66:69], v[50:53], v[100:103], v[66:69]
	ds_read_b128 v[100:103], v6 offset:13184
	ds_read_b128 v[116:119], v6 offset:13248
	v_mfma_f32_16x16x32_bf16 v[96:99], v[46:49], v[124:127], v[120:123]
	s_waitcnt lgkmcnt(1)
	v_mfma_f32_16x16x32_bf16 v[84:87], v[50:53], v[100:103], v[84:87]
	ds_read_b128 v[100:103], v6 offset:17536
	ds_read_b128 v[120:123], v6 offset:17600
	s_waitcnt lgkmcnt(1)
	v_mfma_f32_16x16x32_bf16 v[88:91], v[50:53], v[100:103], v[88:91]
	ds_read_b128 v[100:103], v6 offset:21888
	ds_read_b128 v[124:127], v6 offset:21952
	v_mfma_f32_16x16x32_bf16 v[58:61], v[54:57], v[104:107], v[58:61]
	v_mfma_f32_16x16x32_bf16 v[62:65], v[54:57], v[108:111], v[62:65]
	s_waitcnt lgkmcnt(1)
	v_mfma_f32_16x16x32_bf16 v[92:95], v[50:53], v[100:103], v[92:95]
	ds_read_b128 v[100:103], v6 offset:26240
	ds_read_b128 v[104:107], v6 offset:26304
	ds_read_b128 v[108:111], v6 offset:30464
	s_nop 2
	ds_write2_b32 v38, v58, v62 offset1:16
	ds_write2_b32 v38, v59, v63 offset0:133 offset1:149
	ds_write2_b32 v39, v60, v64 offset0:10 offset1:26
	v_mfma_f32_16x16x32_bf16 v[66:69], v[54:57], v[112:115], v[66:69]
	v_mfma_f32_16x16x32_bf16 v[84:87], v[54:57], v[116:119], v[84:87]
	ds_write2_b32 v39, v61, v65 offset0:143 offset1:159
	s_nop 6
	ds_write2_b32 v38, v66, v84 offset0:33 offset1:49
	ds_read_b128 v[58:61], v6 offset:30528
	s_waitcnt lgkmcnt(6)
	v_mfma_f32_16x16x32_bf16 v[42:45], v[42:45], v[108:111], 0
	ds_write2_b32 v38, v67, v85 offset0:166 offset1:182
	ds_write2_b32 v39, v68, v86 offset0:43 offset1:59
	ds_read_b128 v[62:65], v6 offset:30592
	v_mfma_f32_16x16x32_bf16 v[88:91], v[54:57], v[120:123], v[88:91]
	v_mfma_f32_16x16x32_bf16 v[92:95], v[54:57], v[124:127], v[92:95]
	ds_write2_b32 v39, v69, v87 offset0:176 offset1:192
	s_nop 6
	ds_write2_b32 v38, v88, v92 offset0:66 offset1:82
	s_waitcnt lgkmcnt(5)
	v_mfma_f32_16x16x32_bf16 v[42:45], v[46:49], v[58:61], v[42:45]
	ds_read_b128 v[46:49], v6 offset:30656
	ds_write2_b32 v38, v89, v93 offset0:199 offset1:215
	ds_write2_b32 v39, v90, v94 offset0:76 offset1:92
	ds_write2_b32 v39, v91, v95 offset0:209 offset1:225
	v_mfma_f32_16x16x32_bf16 v[96:99], v[50:53], v[100:103], v[96:99]
	s_waitcnt lgkmcnt(6)
	v_mfma_f32_16x16x32_bf16 v[42:45], v[50:53], v[62:65], v[42:45]
	v_mfma_f32_16x16x32_bf16 v[96:99], v[54:57], v[104:107], v[96:99]
	s_waitcnt lgkmcnt(3)
	v_mfma_f32_16x16x32_bf16 v[42:45], v[54:57], v[46:49], v[42:45]
	s_nop 7
	ds_write2_b32 v38, v96, v42 offset0:99 offset1:115
	ds_write2_b32 v38, v97, v43 offset0:232 offset1:248
	ds_write2_b32 v39, v98, v44 offset0:109 offset1:125
	ds_write2_b32 v40, v99, v45 offset0:114 offset1:130
	s_waitcnt lgkmcnt(0)
	s_nop 0
	ds_read2_b32 v[42:43], v22 offset1:1
	ds_read2_b32 v[44:45], v23 offset1:1
	ds_read2_b32 v[46:47], v24 offset1:1
	ds_read2_b32 v[48:49], v25 offset1:1
	s_waitcnt lgkmcnt(3)
	v_not_b32_e32 v0, v42
	v_or_b32_e32 v50, 0x80000000, v42
	v_cmp_gt_i32_e64 s[0:1], 0, v42
	s_waitcnt lgkmcnt(2)
	v_not_b32_e32 v42, v44
	v_cndmask_b32_e64 v0, v50, v0, s[0:1]
	v_or_b32_e32 v50, 0x80000000, v44
	v_cmp_gt_i32_e64 s[0:1], 0, v44
	v_or_b32_e32 v44, 0x80000000, v43
	v_and_b32_e32 v0, 0xffffff80, v0
	v_cndmask_b32_e64 v42, v50, v42, s[0:1]
	v_and_b32_e32 v42, 0xffffff80, v42
	v_sub_u32_e32 v42, v42, v78
	v_add_u32_e32 v50, 0x6f, v42
	v_not_b32_e32 v42, v43
	v_cmp_gt_i32_e64 s[0:1], 0, v43
	v_or_b32_e32 v43, 0x80000000, v45
	v_sub_u32_e32 v0, v0, v78
	v_cndmask_b32_e64 v42, v44, v42, s[0:1]
	v_and_b32_e32 v42, 0xffffff80, v42
	v_sub_u32_e32 v42, v42, v7
	v_add_u32_e32 v51, 0x7f, v42
	v_not_b32_e32 v42, v45
	v_cmp_gt_i32_e64 s[0:1], 0, v45
	v_add_u32_e32 v0, 0x7f, v0
	s_nop 0
	v_cndmask_b32_e64 v42, v43, v42, s[0:1]
	v_and_b32_e32 v42, 0xffffff80, v42
	v_sub_u32_e32 v42, v42, v7
	v_add_u32_e32 v52, 0x6f, v42
	s_waitcnt lgkmcnt(1)
	v_not_b32_e32 v42, v46
	v_or_b32_e32 v43, 0x80000000, v46
	v_cmp_gt_i32_e64 s[0:1], 0, v46
	v_max_u32_e32 v89, v50, v52
	v_min_u32_e32 v50, v50, v52
	v_cndmask_b32_e64 v42, v43, v42, s[0:1]
	v_and_b32_e32 v42, 0xffffff80, v42
	v_sub_u32_e32 v42, v42, v8
	v_add_u32_e32 v53, 0x7f, v42
	s_waitcnt lgkmcnt(0)
	v_not_b32_e32 v42, v48
	v_or_b32_e32 v43, 0x80000000, v48
	v_cmp_gt_i32_e64 s[0:1], 0, v48
	s_nop 1
	v_cndmask_b32_e64 v42, v43, v42, s[0:1]
	v_and_b32_e32 v42, 0xffffff80, v42
	v_sub_u32_e32 v42, v42, v8
	v_add_u32_e32 v54, 0x6f, v42
	v_not_b32_e32 v42, v47
	v_or_b32_e32 v43, 0x80000000, v47
	v_cmp_gt_i32_e64 s[0:1], 0, v47
	s_nop 1
	v_cndmask_b32_e64 v42, v43, v42, s[0:1]
	v_and_b32_e32 v42, 0xffffff80, v42
	v_sub_u32_e32 v42, v42, v9
	v_add_u32_e32 v55, 0x7f, v42
	v_not_b32_e32 v42, v49
	v_or_b32_e32 v43, 0x80000000, v49
	v_cmp_gt_i32_e64 s[0:1], 0, v49
	s_nop 1
	v_cndmask_b32_e64 v42, v43, v42, s[0:1]
	v_and_b32_e32 v42, 0xffffff80, v42
	v_sub_u32_e32 v44, v42, v9
	ds_read2_b32 v[42:43], v26 offset1:1
	v_add_u32_e32 v56, 0x6f, v44
	ds_read2_b32 v[44:45], v27 offset1:1
	ds_read2_b32 v[46:47], v28 offset1:1
	ds_read2_b32 v[48:49], v29 offset1:1
	v_max_u32_e32 v52, v56, v54
	v_min_u32_e32 v54, v56, v54
	s_waitcnt lgkmcnt(3)
	v_not_b32_e32 v57, v42
	v_or_b32_e32 v58, 0x80000000, v42
	v_cmp_gt_i32_e64 s[0:1], 0, v42
	s_nop 1
	v_cndmask_b32_e64 v42, v58, v57, s[0:1]
	v_and_b32_e32 v42, 0xffffff80, v42
	v_sub_u32_e32 v42, v42, v10
	v_add_u32_e32 v57, 0x7f, v42
	s_waitcnt lgkmcnt(2)
	v_not_b32_e32 v42, v44
	v_or_b32_e32 v58, 0x80000000, v44
	v_cmp_gt_i32_e64 s[0:1], 0, v44
	v_or_b32_e32 v44, 0x80000000, v43
	s_nop 0
	v_cndmask_b32_e64 v42, v58, v42, s[0:1]
	v_and_b32_e32 v42, 0xffffff80, v42
	v_sub_u32_e32 v42, v42, v10
	v_add_u32_e32 v58, 0x6f, v42
	v_not_b32_e32 v42, v43
	v_cmp_gt_i32_e64 s[0:1], 0, v43
	v_or_b32_e32 v43, 0x80000000, v45
	s_nop 0
	v_cndmask_b32_e64 v42, v44, v42, s[0:1]
	v_and_b32_e32 v42, 0xffffff80, v42
	v_sub_u32_e32 v42, v42, v11
	v_add_u32_e32 v59, 0x7f, v42
	v_not_b32_e32 v42, v45
	v_cmp_gt_i32_e64 s[0:1], 0, v45
	s_nop 1
	v_cndmask_b32_e64 v42, v43, v42, s[0:1]
	v_and_b32_e32 v42, 0xffffff80, v42
	v_sub_u32_e32 v42, v42, v11
	v_add_u32_e32 v60, 0x6f, v42
	s_waitcnt lgkmcnt(1)
	v_not_b32_e32 v42, v46
	v_or_b32_e32 v43, 0x80000000, v46
	v_cmp_gt_i32_e64 s[0:1], 0, v46
	v_max_u32_e32 v56, v58, v60
	v_min_u32_e32 v58, v58, v60
	v_cndmask_b32_e64 v42, v43, v42, s[0:1]
	v_and_b32_e32 v42, 0xffffff80, v42
	v_sub_u32_e32 v42, v42, v12
	v_add_u32_e32 v61, 0x7f, v42
	s_waitcnt lgkmcnt(0)
	v_not_b32_e32 v42, v48
	v_or_b32_e32 v43, 0x80000000, v48
	v_cmp_gt_i32_e64 s[0:1], 0, v48
	s_nop 1
	v_cndmask_b32_e64 v42, v43, v42, s[0:1]
	v_and_b32_e32 v42, 0xffffff80, v42
	v_sub_u32_e32 v42, v42, v12
	v_add_u32_e32 v62, 0x6f, v42
	v_not_b32_e32 v42, v47
	v_or_b32_e32 v43, 0x80000000, v47
	v_cmp_gt_i32_e64 s[0:1], 0, v47
	s_nop 1
	v_cndmask_b32_e64 v42, v43, v42, s[0:1]
	v_and_b32_e32 v42, 0xffffff80, v42
	v_sub_u32_e32 v42, v42, v13
	v_add_u32_e32 v63, 0x7f, v42
	v_not_b32_e32 v42, v49
	v_or_b32_e32 v43, 0x80000000, v49
	v_cmp_gt_i32_e64 s[0:1], 0, v49
	s_nop 1
	v_cndmask_b32_e64 v42, v43, v42, s[0:1]
	v_and_b32_e32 v42, 0xffffff80, v42
	v_sub_u32_e32 v44, v42, v13
	ds_read2_b32 v[42:43], v30 offset1:1
	v_add_u32_e32 v64, 0x6f, v44
	ds_read2_b32 v[44:45], v31 offset1:1
	ds_read2_b32 v[46:47], v32 offset1:1
	ds_read2_b32 v[48:49], v33 offset1:1
	v_max_u32_e32 v60, v64, v62
	v_min_u32_e32 v62, v64, v62
	s_waitcnt lgkmcnt(3)
	v_not_b32_e32 v65, v42
	v_or_b32_e32 v66, 0x80000000, v42
	v_cmp_gt_i32_e64 s[0:1], 0, v42
	s_nop 1
	v_cndmask_b32_e64 v42, v66, v65, s[0:1]
	v_and_b32_e32 v42, 0xffffff80, v42
	v_sub_u32_e32 v42, v42, v14
	v_add_u32_e32 v65, 0x7f, v42
	s_waitcnt lgkmcnt(2)
	v_not_b32_e32 v42, v44
	v_or_b32_e32 v66, 0x80000000, v44
	v_cmp_gt_i32_e64 s[0:1], 0, v44
	v_or_b32_e32 v44, 0x80000000, v43
	s_nop 0
	v_cndmask_b32_e64 v42, v66, v42, s[0:1]
	v_and_b32_e32 v42, 0xffffff80, v42
	v_sub_u32_e32 v42, v42, v14
	v_add_u32_e32 v66, 0x6f, v42
	v_not_b32_e32 v42, v43
	v_cmp_gt_i32_e64 s[0:1], 0, v43
	v_or_b32_e32 v43, 0x80000000, v45
	s_nop 0
	v_cndmask_b32_e64 v42, v44, v42, s[0:1]
	v_and_b32_e32 v42, 0xffffff80, v42
	v_sub_u32_e32 v42, v42, v15
	v_add_u32_e32 v67, 0x7f, v42
	v_not_b32_e32 v42, v45
	v_cmp_gt_i32_e64 s[0:1], 0, v45
	s_nop 1
	v_cndmask_b32_e64 v42, v43, v42, s[0:1]
	v_and_b32_e32 v42, 0xffffff80, v42
	v_sub_u32_e32 v42, v42, v15
	v_add_u32_e32 v68, 0x6f, v42
	s_waitcnt lgkmcnt(1)
	v_not_b32_e32 v42, v46
	v_or_b32_e32 v43, 0x80000000, v46
	v_cmp_gt_i32_e64 s[0:1], 0, v46
	v_max_u32_e32 v64, v66, v68
	v_min_u32_e32 v66, v66, v68
	v_cndmask_b32_e64 v42, v43, v42, s[0:1]
	v_and_b32_e32 v42, 0xffffff80, v42
	v_sub_u32_e32 v42, v42, v16
	v_add_u32_e32 v69, 0x7f, v42
	s_waitcnt lgkmcnt(0)
	v_not_b32_e32 v42, v48
	v_or_b32_e32 v43, 0x80000000, v48
	v_cmp_gt_i32_e64 s[0:1], 0, v48
	s_nop 1
	v_cndmask_b32_e64 v42, v43, v42, s[0:1]
	v_and_b32_e32 v42, 0xffffff80, v42
	v_sub_u32_e32 v42, v42, v16
	v_add_u32_e32 v70, 0x6f, v42
	v_not_b32_e32 v42, v47
	v_or_b32_e32 v43, 0x80000000, v47
	v_cmp_gt_i32_e64 s[0:1], 0, v47
	s_nop 1
	v_cndmask_b32_e64 v42, v43, v42, s[0:1]
	v_and_b32_e32 v42, 0xffffff80, v42
	v_sub_u32_e32 v42, v42, v17
	v_add_u32_e32 v71, 0x7f, v42
	v_not_b32_e32 v42, v49
	v_or_b32_e32 v43, 0x80000000, v49
	v_cmp_gt_i32_e64 s[0:1], 0, v49
	s_nop 1
	v_cndmask_b32_e64 v42, v43, v42, s[0:1]
	v_and_b32_e32 v42, 0xffffff80, v42
	v_sub_u32_e32 v44, v42, v17
	ds_read2_b32 v[42:43], v34 offset1:1
	v_add_u32_e32 v73, 0x6f, v44
	ds_read2_b32 v[44:45], v35 offset1:1
	ds_read2_b32 v[46:47], v36 offset1:1
	ds_read2_b32 v[48:49], v37 offset1:1
	v_max_u32_e32 v68, v73, v70
	v_min_u32_e32 v70, v73, v70
	s_waitcnt lgkmcnt(3)
	v_not_b32_e32 v77, v42
	v_or_b32_e32 v80, 0x80000000, v42
	v_cmp_gt_i32_e64 s[0:1], 0, v42
	s_nop 1
	v_cndmask_b32_e64 v42, v80, v77, s[0:1]
	s_waitcnt lgkmcnt(2)
	v_not_b32_e32 v77, v44
	v_or_b32_e32 v80, 0x80000000, v44
	v_cmp_gt_i32_e64 s[0:1], 0, v44
	v_and_b32_e32 v42, 0xffffff80, v42
	v_sub_u32_e32 v42, v42, v18
	v_cndmask_b32_e64 v44, v80, v77, s[0:1]
	v_not_b32_e32 v77, v43
	v_or_b32_e32 v80, 0x80000000, v43
	v_cmp_gt_i32_e64 s[0:1], 0, v43
	v_and_b32_e32 v44, 0xffffff80, v44
	v_sub_u32_e32 v44, v44, v18
	v_cndmask_b32_e64 v43, v80, v77, s[0:1]
	v_not_b32_e32 v77, v45
	v_or_b32_e32 v80, 0x80000000, v45
	v_cmp_gt_i32_e64 s[0:1], 0, v45
	v_and_b32_e32 v43, 0xffffff80, v43
	v_sub_u32_e32 v43, v43, v19
	v_cndmask_b32_e64 v45, v80, v77, s[0:1]
	s_waitcnt lgkmcnt(1)
	v_not_b32_e32 v77, v46
	v_or_b32_e32 v80, 0x80000000, v46
	v_cmp_gt_i32_e64 s[0:1], 0, v46
	v_and_b32_e32 v45, 0xffffff80, v45
	v_sub_u32_e32 v45, v45, v19
	v_cndmask_b32_e64 v46, v80, v77, s[0:1]
	s_waitcnt lgkmcnt(0)
	v_not_b32_e32 v77, v48
	v_or_b32_e32 v80, 0x80000000, v48
	v_cmp_gt_i32_e64 s[0:1], 0, v48
	v_and_b32_e32 v46, 0xffffff80, v46
	v_sub_u32_e32 v46, v46, v20
	v_cndmask_b32_e64 v48, v80, v77, s[0:1]
	v_not_b32_e32 v77, v47
	v_or_b32_e32 v80, 0x80000000, v47
	v_cmp_gt_i32_e64 s[0:1], 0, v47
	v_and_b32_e32 v48, 0xffffff80, v48
	v_sub_u32_e32 v48, v48, v20
	v_cndmask_b32_e64 v47, v80, v77, s[0:1]
	v_not_b32_e32 v77, v49
	v_or_b32_e32 v80, 0x80000000, v49
	v_cmp_gt_i32_e64 s[0:1], 0, v49
	v_and_b32_e32 v47, 0xffffff80, v47
	v_sub_u32_e32 v47, v47, v21
	v_cndmask_b32_e64 v49, v80, v77, s[0:1]
	v_and_b32_e32 v49, 0xffffff80, v49
	v_sub_u32_e32 v49, v49, v21
	v_add_u32_e32 v42, 0x7f, v42
	v_add_u32_e32 v44, 0x6f, v44
	v_add_u32_e32 v43, 0x7f, v43
	v_add_u32_e32 v45, 0x6f, v45
	v_add_u32_e32 v46, 0x7f, v46
	v_add_u32_e32 v48, 0x6f, v48
	v_add_u32_e32 v47, 0x7f, v47
	v_add_u32_e32 v49, 0x6f, v49
	v_max_u32_e32 v77, v0, v51
	v_min_u32_e32 v0, v0, v51
	v_max_u32_e32 v51, v55, v53
	v_min_u32_e32 v53, v55, v53
	v_max_u32_e32 v55, v57, v59
	v_min_u32_e32 v57, v57, v59
	v_max_u32_e32 v59, v63, v61
	v_min_u32_e32 v61, v63, v61
	v_max_u32_e32 v63, v65, v67
	v_min_u32_e32 v65, v65, v67
	v_max_u32_e32 v67, v71, v69
	v_min_u32_e32 v69, v71, v69
	v_max_u32_e32 v71, v42, v43
	v_min_u32_e32 v42, v42, v43
	v_max_u32_e32 v43, v47, v46
	v_min_u32_e32 v46, v47, v46
	v_max_u32_e32 v73, v44, v45
	v_min_u32_e32 v44, v44, v45
	v_max_u32_e32 v45, v49, v48
	v_min_u32_e32 v48, v49, v48
	v_max_u32_e32 v47, v77, v53
	v_min_u32_e32 v53, v77, v53
	v_max_u32_e32 v77, v0, v51
	v_min_u32_e32 v0, v0, v51
	v_max_u32_e32 v51, v61, v55
	v_min_u32_e32 v55, v61, v55
	v_max_u32_e32 v61, v59, v57
	v_min_u32_e32 v57, v59, v57
	v_max_u32_e32 v59, v63, v69
	v_min_u32_e32 v63, v63, v69
	v_max_u32_e32 v69, v65, v67
	v_min_u32_e32 v65, v65, v67
	v_max_u32_e32 v67, v46, v71
	v_min_u32_e32 v46, v46, v71
	v_max_u32_e32 v71, v43, v42
	v_min_u32_e32 v42, v43, v42
	v_max_u32_e32 v49, v89, v54
	v_min_u32_e32 v54, v89, v54
	v_max_u32_e32 v89, v50, v52
	v_min_u32_e32 v50, v50, v52
	v_max_u32_e32 v52, v62, v56
	v_min_u32_e32 v56, v62, v56
	v_max_u32_e32 v62, v60, v58
	v_min_u32_e32 v58, v60, v58
	v_max_u32_e32 v60, v64, v70
	v_min_u32_e32 v64, v64, v70
	v_max_u32_e32 v70, v66, v68
	v_min_u32_e32 v66, v66, v68
	v_max_u32_e32 v68, v48, v73
	v_min_u32_e32 v48, v48, v73
	v_max_u32_e32 v73, v45, v44
	v_min_u32_e32 v44, v45, v44
	v_max_u32_e32 v43, v47, v77
	v_min_u32_e32 v47, v47, v77
	v_max_u32_e32 v77, v53, v0
	v_min_u32_e32 v0, v53, v0
	v_max_u32_e32 v53, v57, v55
	v_min_u32_e32 v55, v57, v55
	v_max_u32_e32 v57, v61, v51
	v_min_u32_e32 v51, v61, v51
	v_max_u32_e32 v61, v59, v69
	v_min_u32_e32 v59, v59, v69
	v_max_u32_e32 v69, v63, v65
	v_min_u32_e32 v63, v63, v65
	v_max_u32_e32 v65, v42, v46
	v_min_u32_e32 v42, v42, v46
	v_max_u32_e32 v46, v71, v67
	v_min_u32_e32 v67, v71, v67
	v_max_u32_e32 v45, v49, v89
	v_min_u32_e32 v49, v49, v89
	v_max_u32_e32 v89, v54, v50
	v_min_u32_e32 v50, v54, v50
	v_max_u32_e32 v54, v58, v56
	v_min_u32_e32 v56, v58, v56
	v_max_u32_e32 v58, v62, v52
	v_min_u32_e32 v52, v62, v52
	v_max_u32_e32 v62, v60, v70
	v_min_u32_e32 v60, v60, v70
	v_max_u32_e32 v70, v64, v66
	v_min_u32_e32 v64, v64, v66
	v_max_u32_e32 v66, v44, v48
	v_min_u32_e32 v44, v44, v48
	v_max_u32_e32 v48, v73, v68
	v_min_u32_e32 v68, v73, v68
	v_max_u32_e32 v71, v43, v55
	v_min_u32_e32 v43, v43, v55
	v_max_u32_e32 v55, v47, v53
	v_min_u32_e32 v47, v47, v53
	v_max_u32_e32 v53, v77, v51
	v_min_u32_e32 v51, v77, v51
	v_max_u32_e32 v77, v0, v57
	v_min_u32_e32 v0, v0, v57
	v_max_u32_e32 v57, v42, v61
	v_min_u32_e32 v42, v42, v61
	v_max_u32_e32 v61, v65, v59
	v_min_u32_e32 v59, v65, v59
	v_max_u32_e32 v65, v67, v69
	v_min_u32_e32 v67, v67, v69
	v_max_u32_e32 v69, v46, v63
	v_min_u32_e32 v46, v46, v63
	v_max_u32_e32 v73, v45, v56
	v_min_u32_e32 v45, v45, v56
	v_max_u32_e32 v56, v49, v54
	v_min_u32_e32 v49, v49, v54
	v_max_u32_e32 v54, v89, v52
	v_min_u32_e32 v52, v89, v52
	v_max_u32_e32 v89, v50, v58
	v_min_u32_e32 v50, v50, v58
	v_max_u32_e32 v58, v44, v62
	v_min_u32_e32 v44, v44, v62
	v_max_u32_e32 v62, v66, v60
	v_min_u32_e32 v60, v66, v60
	v_max_u32_e32 v66, v68, v70
	v_min_u32_e32 v68, v68, v70
	v_max_u32_e32 v70, v48, v64
	v_min_u32_e32 v48, v48, v64
	v_max_u32_e32 v63, v71, v53
	v_min_u32_e32 v53, v71, v53
	v_max_u32_e32 v71, v55, v77
	v_min_u32_e32 v55, v55, v77
	v_max_u32_e32 v77, v43, v51
	v_min_u32_e32 v43, v43, v51
	v_max_u32_e32 v51, v47, v0
	v_min_u32_e32 v0, v47, v0
	v_max_u32_e32 v47, v67, v42
	v_min_u32_e32 v42, v67, v42
	v_max_u32_e32 v67, v46, v59
	v_min_u32_e32 v46, v46, v59
	v_max_u32_e32 v59, v65, v57
	v_min_u32_e32 v57, v65, v57
	v_max_u32_e32 v65, v69, v61
	v_min_u32_e32 v61, v69, v61
	v_max_u32_e32 v64, v73, v54
	v_min_u32_e32 v54, v73, v54
	v_max_u32_e32 v73, v56, v89
	v_min_u32_e32 v56, v56, v89
	v_max_u32_e32 v89, v45, v52
	v_min_u32_e32 v45, v45, v52
	v_max_u32_e32 v52, v49, v50
	v_min_u32_e32 v49, v49, v50
	v_max_u32_e32 v50, v68, v44
	v_min_u32_e32 v44, v68, v44
	v_max_u32_e32 v68, v48, v60
	v_min_u32_e32 v48, v48, v60
	v_max_u32_e32 v60, v66, v58
	v_min_u32_e32 v58, v66, v58
	v_max_u32_e32 v66, v70, v62
	v_min_u32_e32 v62, v70, v62
	v_max_u32_e32 v69, v63, v71
	v_min_u32_e32 v63, v63, v71
	v_max_u32_e32 v71, v53, v55
	v_min_u32_e32 v53, v53, v55
	v_max_u32_e32 v55, v77, v51
	v_min_u32_e32 v51, v77, v51
	v_max_u32_e32 v77, v43, v0
	v_min_u32_e32 v0, v43, v0
	v_max_u32_e32 v43, v46, v42
	v_min_u32_e32 v42, v46, v42
	v_max_u32_e32 v46, v67, v47
	v_min_u32_e32 v47, v67, v47
	v_max_u32_e32 v67, v61, v57
	v_min_u32_e32 v57, v61, v57
	v_max_u32_e32 v61, v65, v59
	v_min_u32_e32 v59, v65, v59
	v_max_u32_e32 v70, v64, v73
	v_min_u32_e32 v64, v64, v73
	v_max_u32_e32 v73, v54, v56
	v_min_u32_e32 v54, v54, v56
	v_max_u32_e32 v56, v89, v52
	v_min_u32_e32 v52, v89, v52
	v_max_u32_e32 v89, v45, v49
	v_min_u32_e32 v45, v45, v49
	v_max_u32_e32 v49, v48, v44
	v_min_u32_e32 v44, v48, v44
	v_max_u32_e32 v48, v68, v50
	v_min_u32_e32 v50, v68, v50
	v_max_u32_e32 v68, v62, v58
	v_min_u32_e32 v58, v62, v58
	v_max_u32_e32 v62, v66, v60
	v_min_u32_e32 v60, v66, v60
	v_max_u32_e32 v65, v69, v42
	v_min_u32_e32 v42, v69, v42
	v_max_u32_e32 v69, v63, v43
	v_min_u32_e32 v43, v63, v43
	v_max_u32_e32 v63, v71, v47
	v_min_u32_e32 v47, v71, v47
	v_max_u32_e32 v71, v53, v46
	v_min_u32_e32 v46, v53, v46
	v_max_u32_e32 v53, v55, v57
	v_min_u32_e32 v55, v55, v57
	v_max_u32_e32 v57, v51, v67
	v_min_u32_e32 v51, v51, v67
	v_max_u32_e32 v67, v77, v59
	v_min_u32_e32 v59, v77, v59
	v_max_u32_e32 v77, v0, v61
	v_min_u32_e32 v0, v0, v61
	v_max_u32_e32 v66, v70, v44
	v_min_u32_e32 v44, v70, v44
	v_max_u32_e32 v70, v64, v49
	v_min_u32_e32 v49, v64, v49
	v_max_u32_e32 v64, v73, v50
	v_min_u32_e32 v50, v73, v50
	v_max_u32_e32 v73, v54, v48
	v_min_u32_e32 v48, v54, v48
	v_max_u32_e32 v54, v56, v58
	v_min_u32_e32 v56, v56, v58
	v_max_u32_e32 v58, v52, v68
	v_min_u32_e32 v52, v52, v68
	v_max_u32_e32 v68, v89, v60
	v_min_u32_e32 v60, v89, v60
	v_max_u32_e32 v89, v45, v62
	v_min_u32_e32 v45, v45, v62
	v_max_u32_e32 v61, v65, v53
	v_min_u32_e32 v53, v65, v53
	v_max_u32_e32 v65, v69, v57
	v_min_u32_e32 v57, v69, v57
	v_max_u32_e32 v69, v63, v67
	v_min_u32_e32 v63, v63, v67
	v_max_u32_e32 v67, v71, v77
	v_min_u32_e32 v71, v71, v77
	v_max_u32_e32 v77, v42, v55
	v_min_u32_e32 v42, v42, v55
	v_max_u32_e32 v55, v43, v51
	v_min_u32_e32 v43, v43, v51
	v_max_u32_e32 v51, v47, v59
	v_min_u32_e32 v47, v47, v59
	v_max_u32_e32 v59, v46, v0
	v_min_u32_e32 v0, v46, v0
	v_max_u32_e32 v62, v66, v54
	v_min_u32_e32 v54, v66, v54
	v_max_u32_e32 v66, v70, v58
	v_min_u32_e32 v58, v70, v58
	v_max_u32_e32 v70, v64, v68
	v_min_u32_e32 v64, v64, v68
	v_max_u32_e32 v68, v73, v89
	v_min_u32_e32 v73, v73, v89
	v_max_u32_e32 v89, v44, v56
	v_min_u32_e32 v44, v44, v56
	v_max_u32_e32 v56, v49, v52
	v_min_u32_e32 v49, v49, v52
	v_max_u32_e32 v52, v50, v60
	v_min_u32_e32 v50, v50, v60
	v_max_u32_e32 v60, v48, v45
	v_min_u32_e32 v45, v48, v45
	v_max_u32_e32 v46, v61, v69
	v_min_u32_e32 v61, v61, v69
	v_max_u32_e32 v69, v65, v67
	v_min_u32_e32 v65, v65, v67
	v_max_u32_e32 v67, v53, v63
	v_min_u32_e32 v53, v53, v63
	v_max_u32_e32 v63, v57, v71
	v_min_u32_e32 v57, v57, v71
	v_max_u32_e32 v71, v77, v51
	v_min_u32_e32 v51, v77, v51
	v_max_u32_e32 v77, v55, v59
	v_min_u32_e32 v55, v55, v59
	v_max_u32_e32 v59, v42, v47
	v_min_u32_e32 v42, v42, v47
	v_max_u32_e32 v47, v43, v0
	v_min_u32_e32 v0, v43, v0
	v_max_u32_e32 v48, v62, v70
	v_min_u32_e32 v62, v62, v70
	v_max_u32_e32 v70, v66, v68
	v_min_u32_e32 v66, v66, v68
	v_max_u32_e32 v68, v54, v64
	v_min_u32_e32 v54, v54, v64
	v_max_u32_e32 v64, v58, v73
	v_min_u32_e32 v58, v58, v73
	v_max_u32_e32 v73, v89, v52
	v_min_u32_e32 v52, v89, v52
	v_max_u32_e32 v89, v56, v60
	v_min_u32_e32 v56, v56, v60
	v_max_u32_e32 v60, v44, v50
	v_min_u32_e32 v44, v44, v50
	v_max_u32_e32 v50, v49, v45
	v_min_u32_e32 v45, v49, v45
	v_min_u32_e32 v43, v46, v69
	v_min_u32_e32 v80, v61, v65
	v_min_u32_e32 v82, v67, v63
	v_min_u32_e32 v84, v53, v57
	v_min_u32_e32 v85, v71, v77
	v_min_u32_e32 v86, v51, v55
	v_min_u32_e32 v87, v59, v47
	v_min_u32_e32 v88, v42, v0
	v_min_u32_e32 v49, v48, v70
	v_min_u32_e32 v90, v62, v66
	v_min_u32_e32 v91, v68, v64
	v_min_u32_e32 v92, v54, v58
	v_min_u32_e32 v93, v73, v89
	v_min_u32_e32 v94, v52, v56
	v_min_u32_e32 v95, v60, v50
	v_min_u32_e32 v96, v44, v45
	v_max3_u32 v46, v46, v69, v96
	v_max3_u32 v43, v43, v44, v45
	v_max3_u32 v44, v61, v65, v95
	v_max3_u32 v45, v80, v60, v50
	v_max3_u32 v50, v67, v63, v94
	v_max3_u32 v52, v82, v52, v56
	v_max3_u32 v53, v53, v57, v93
	v_max3_u32 v56, v84, v73, v89
	v_max3_u32 v57, v71, v77, v92
	v_max3_u32 v54, v85, v54, v58
	v_max3_u32 v51, v51, v55, v91
	v_max3_u32 v55, v86, v68, v64
	v_max3_u32 v47, v59, v47, v90
	v_max3_u32 v58, v87, v62, v66
	v_max3_u32 v0, v42, v0, v49
	v_max3_u32 v42, v88, v48, v70
	v_max_u32_e32 v48, v46, v57
	v_min_u32_e32 v46, v46, v57
	v_max_u32_e32 v49, v43, v54
	v_min_u32_e32 v43, v43, v54
	v_max_u32_e32 v54, v44, v51
	v_min_u32_e32 v44, v44, v51
	v_max_u32_e32 v51, v45, v55
	v_min_u32_e32 v45, v45, v55
	v_max_u32_e32 v55, v50, v47
	v_min_u32_e32 v47, v50, v47
	v_max_u32_e32 v50, v52, v58
	v_min_u32_e32 v52, v52, v58
	v_max_u32_e32 v57, v53, v0
	v_min_u32_e32 v0, v53, v0
	v_max_u32_e32 v53, v56, v42
	v_min_u32_e32 v42, v56, v42
	v_max_u32_e32 v56, v48, v55
	v_min_u32_e32 v48, v48, v55
	v_max_u32_e32 v55, v49, v50
	v_min_u32_e32 v49, v49, v50
	v_max_u32_e32 v50, v54, v57
	v_min_u32_e32 v54, v54, v57
	v_max_u32_e32 v57, v51, v53
	v_min_u32_e32 v51, v51, v53
	v_max_u32_e32 v53, v46, v47
	v_min_u32_e32 v46, v46, v47
	v_max_u32_e32 v47, v43, v52
	v_min_u32_e32 v43, v43, v52
	v_max_u32_e32 v52, v44, v0
	v_min_u32_e32 v0, v44, v0
	v_max_u32_e32 v44, v45, v42
	v_min_u32_e32 v42, v45, v42
	v_max_u32_e32 v45, v56, v50
	v_min_u32_e32 v50, v56, v50
	v_max_u32_e32 v56, v55, v57
	v_min_u32_e32 v55, v55, v57
	v_max_u32_e32 v57, v48, v54
	v_min_u32_e32 v48, v48, v54
	v_max_u32_e32 v54, v49, v51
	v_min_u32_e32 v49, v49, v51
	v_max_u32_e32 v51, v53, v52
	v_min_u32_e32 v52, v53, v52
	v_max_u32_e32 v53, v47, v44
	v_min_u32_e32 v44, v47, v44
	v_max_u32_e32 v47, v46, v0
	v_min_u32_e32 v0, v46, v0
	v_max_u32_e32 v46, v43, v42
	v_min_u32_e32 v42, v43, v42
	v_max_u32_e32 v43, v45, v56
	v_min_u32_e32 v45, v45, v56
	v_max_u32_e32 v56, v50, v55
	v_min_u32_e32 v50, v50, v55
	v_max_u32_e32 v55, v57, v54
	v_min_u32_e32 v54, v57, v54
	v_max_u32_e32 v57, v48, v49
	v_min_u32_e32 v48, v48, v49
	v_max_u32_e32 v49, v51, v53
	v_min_u32_e32 v51, v51, v53
	v_max_u32_e32 v53, v52, v44
	v_min_u32_e32 v44, v52, v44
	v_max_u32_e32 v52, v47, v46
	v_min_u32_e32 v46, v47, v46
	v_max_u32_e32 v47, v0, v42
	v_min_u32_e32 v0, v0, v42
	v_max_u32_dpp v59, v46, v56 quad_perm:[1,0,3,2] row_mask:0xf bank_mask:0xf bound_ctrl:1
	v_max_u32_dpp v58, v47, v45 quad_perm:[1,0,3,2] row_mask:0xf bank_mask:0xf bound_ctrl:1
	v_max_u32_dpp v42, v0, v43 quad_perm:[1,0,3,2] row_mask:0xf bank_mask:0xf bound_ctrl:1
	v_max_u32_dpp v60, v52, v50 quad_perm:[1,0,3,2] row_mask:0xf bank_mask:0xf bound_ctrl:1
	v_max_u32_dpp v61, v44, v55 quad_perm:[1,0,3,2] row_mask:0xf bank_mask:0xf bound_ctrl:1
	v_max_u32_dpp v62, v53, v54 quad_perm:[1,0,3,2] row_mask:0xf bank_mask:0xf bound_ctrl:1
	v_max_u32_dpp v63, v51, v57 quad_perm:[1,0,3,2] row_mask:0xf bank_mask:0xf bound_ctrl:1
	v_max_u32_dpp v64, v49, v48 quad_perm:[1,0,3,2] row_mask:0xf bank_mask:0xf bound_ctrl:1
	v_max_u32_dpp v48, v48, v49 quad_perm:[1,0,3,2] row_mask:0xf bank_mask:0xf bound_ctrl:1
	v_max_u32_dpp v49, v57, v51 quad_perm:[1,0,3,2] row_mask:0xf bank_mask:0xf bound_ctrl:1
	v_max_u32_dpp v51, v54, v53 quad_perm:[1,0,3,2] row_mask:0xf bank_mask:0xf bound_ctrl:1
	v_max_u32_dpp v44, v55, v44 quad_perm:[1,0,3,2] row_mask:0xf bank_mask:0xf bound_ctrl:1
	v_max_u32_dpp v50, v50, v52 quad_perm:[1,0,3,2] row_mask:0xf bank_mask:0xf bound_ctrl:1
	v_max_u32_dpp v46, v56, v46 quad_perm:[1,0,3,2] row_mask:0xf bank_mask:0xf bound_ctrl:1
	v_max_u32_dpp v45, v45, v47 quad_perm:[1,0,3,2] row_mask:0xf bank_mask:0xf bound_ctrl:1
	v_max_u32_dpp v0, v43, v0 quad_perm:[1,0,3,2] row_mask:0xf bank_mask:0xf bound_ctrl:1
	v_max_u32_e32 v43, v42, v48
	v_min_u32_e32 v42, v42, v48
	v_max_u32_e32 v47, v58, v49
	v_min_u32_e32 v48, v58, v49
	v_max_u32_e32 v49, v59, v51
	v_min_u32_e32 v51, v59, v51
	v_max_u32_e32 v52, v60, v44
	v_min_u32_e32 v44, v60, v44
	v_max_u32_e32 v53, v61, v50
	v_min_u32_e32 v50, v61, v50
	v_max_u32_e32 v54, v62, v46
	v_min_u32_e32 v46, v62, v46
	v_max_u32_e32 v55, v63, v45
	v_min_u32_e32 v45, v63, v45
	v_max_u32_e32 v56, v64, v0
	v_min_u32_e32 v0, v64, v0
	v_max_u32_e32 v57, v43, v53
	v_min_u32_e32 v43, v43, v53
	v_max_u32_e32 v53, v47, v54
	v_min_u32_e32 v47, v47, v54
	v_max_u32_e32 v54, v49, v55
	v_min_u32_e32 v49, v49, v55
	v_max_u32_e32 v55, v52, v56
	v_min_u32_e32 v52, v52, v56
	v_max_u32_e32 v56, v42, v50
	v_min_u32_e32 v42, v42, v50
	v_max_u32_e32 v50, v48, v46
	v_min_u32_e32 v46, v48, v46
	v_max_u32_e32 v48, v51, v45
	v_min_u32_e32 v45, v51, v45
	v_max_u32_e32 v51, v44, v0
	v_min_u32_e32 v0, v44, v0
	v_max_u32_e32 v44, v57, v54
	v_min_u32_e32 v54, v57, v54
	v_max_u32_e32 v57, v53, v55
	v_min_u32_e32 v53, v53, v55
	v_max_u32_e32 v58, v43, v49
	v_min_u32_e32 v49, v43, v49
	v_max_u32_e32 v59, v47, v52
	v_min_u32_e32 v47, v47, v52
	v_max_u32_e32 v52, v56, v48
	v_min_u32_e32 v60, v56, v48
	v_max_u32_e32 v48, v50, v51
	v_min_u32_e32 v61, v50, v51
	v_max_u32_e32 v64, v42, v45
	v_min_u32_e32 v65, v42, v45
	v_max_u32_e32 v66, v46, v0
	v_min_u32_e32 v46, v46, v0
	v_max_u32_e32 v55, v44, v57
	v_min_u32_e32 v43, v44, v57
	v_max_u32_e32 v50, v54, v53
	v_min_u32_e32 v0, v54, v53
	v_max_u32_e32 v56, v58, v59
	v_min_u32_e32 v44, v58, v59
	v_max_u32_e32 v51, v49, v47
	v_min_u32_e32 v42, v49, v47
	v_max_u32_e32 v62, v52, v48
	v_min_u32_e32 v48, v52, v48
	v_max_u32_e32 v57, v60, v61
	v_min_u32_e32 v45, v60, v61
	v_max_u32_e32 v63, v64, v66
	v_min_u32_e32 v49, v64, v66
	v_max_u32_e32 v58, v65, v46
	v_min_u32_e32 v46, v65, v46
	v_mov_b32_dpp v47, v55 quad_perm:[2,3,0,1] row_mask:0xf bank_mask:0xf bound_ctrl:1
	v_mov_b32_dpp v59, v43 quad_perm:[2,3,0,1] row_mask:0xf bank_mask:0xf bound_ctrl:1
	v_mov_b32_dpp v53, v50 quad_perm:[2,3,0,1] row_mask:0xf bank_mask:0xf bound_ctrl:1
	v_mov_b32_dpp v66, v0 quad_perm:[2,3,0,1] row_mask:0xf bank_mask:0xf bound_ctrl:1
	v_mov_b32_dpp v52, v56 quad_perm:[2,3,0,1] row_mask:0xf bank_mask:0xf bound_ctrl:1
	v_mov_b32_dpp v65, v44 quad_perm:[2,3,0,1] row_mask:0xf bank_mask:0xf bound_ctrl:1
	v_mov_b32_dpp v60, v51 quad_perm:[2,3,0,1] row_mask:0xf bank_mask:0xf bound_ctrl:1
	v_mov_b32_dpp v69, v42 quad_perm:[2,3,0,1] row_mask:0xf bank_mask:0xf bound_ctrl:1
	v_mov_b32_dpp v54, v62 quad_perm:[2,3,0,1] row_mask:0xf bank_mask:0xf bound_ctrl:1
	v_mov_b32_dpp v67, v48 quad_perm:[2,3,0,1] row_mask:0xf bank_mask:0xf bound_ctrl:1
	v_mov_b32_dpp v64, v57 quad_perm:[2,3,0,1] row_mask:0xf bank_mask:0xf bound_ctrl:1
	v_mov_b32_dpp v71, v45 quad_perm:[2,3,0,1] row_mask:0xf bank_mask:0xf bound_ctrl:1
	v_mov_b32_dpp v61, v63 quad_perm:[2,3,0,1] row_mask:0xf bank_mask:0xf bound_ctrl:1
	v_mov_b32_dpp v70, v49 quad_perm:[2,3,0,1] row_mask:0xf bank_mask:0xf bound_ctrl:1
	v_mov_b32_dpp v68, v58 quad_perm:[2,3,0,1] row_mask:0xf bank_mask:0xf bound_ctrl:1
	v_mov_b32_dpp v73, v46 quad_perm:[2,3,0,1] row_mask:0xf bank_mask:0xf bound_ctrl:1
	s_and_saveexec_b64 s[0:1], vcc
	s_cbranch_execz .LBB0_948
	v_max_u32_e32 v55, v55, v73
	v_max_u32_e32 v62, v62, v69
	v_max_u32_e32 v56, v56, v71
	v_max_u32_e32 v63, v63, v66
	v_max_u32_e32 v50, v50, v70
	v_max_u32_e32 v57, v57, v65
	v_max_u32_e32 v51, v51, v67
	v_max_u32_e32 v58, v58, v59
	v_max_u32_e32 v43, v43, v68
	v_max_u32_e32 v48, v48, v60
	v_max_u32_e32 v44, v44, v64
	v_max_u32_e32 v49, v49, v53
	v_max_u32_e32 v0, v0, v61
	v_max_u32_e32 v45, v45, v52
	v_max_u32_e32 v42, v42, v54
	v_max_u32_e32 v46, v46, v47
	v_min_u32_e32 v69, v55, v62
	v_min_u32_e32 v66, v56, v63
	v_min_u32_e32 v65, v50, v57
	v_min_u32_e32 v59, v51, v58
	v_min_u32_e32 v60, v43, v48
	v_min_u32_e32 v53, v44, v49
	v_min_u32_e32 v52, v0, v45
	v_min_u32_e32 v47, v42, v46
	v_min_u32_e32 v71, v69, v66
	v_min_u32_e32 v67, v65, v59
	v_min_u32_e32 v64, v60, v53
	v_min_u32_e32 v54, v52, v47
	v_min_u32_e32 v70, v71, v67
	v_min_u32_e32 v61, v64, v54
	v_max_u32_e32 v67, v71, v67
	v_max_u32_e32 v54, v64, v54
	v_min_u32_e32 v64, v67, v54
	v_max_u32_e32 v67, v67, v54
	v_max_u32_e32 v54, v69, v66
	v_max_u32_e32 v59, v65, v59
	v_max_u32_e32 v53, v60, v53
	v_max_u32_e32 v47, v52, v47
	v_min_u32_e32 v65, v54, v59
	v_min_u32_e32 v52, v53, v47
	v_min_u32_e32 v60, v65, v52
	v_max_u32_e32 v65, v65, v52
	v_max_u32_e32 v52, v54, v59
	v_max_u32_e32 v47, v53, v47
	v_min_u32_e32 v59, v52, v47
	v_max_u32_e32 v66, v52, v47
	v_max_u32_e32 v47, v55, v62
	v_max_u32_e32 v52, v56, v63
	v_max_u32_e32 v50, v50, v57
	v_max_u32_e32 v51, v51, v58
	v_max_u32_e32 v43, v43, v48
	v_max_u32_e32 v44, v44, v49
	v_max_u32_e32 v0, v0, v45
	v_max_u32_e32 v42, v42, v46
	v_min_u32_e32 v53, v47, v52
	v_min_u32_e32 v54, v50, v51
	v_min_u32_e32 v48, v43, v44
	v_min_u32_e32 v45, v0, v42
	v_min_u32_e32 v55, v53, v54
	v_min_u32_e32 v46, v48, v45
	v_min_u32_e32 v49, v55, v46
	v_max_u32_e32 v55, v55, v46
	v_max_u32_e32 v46, v53, v54
	v_max_u32_e32 v45, v48, v45
	v_min_u32_e32 v48, v46, v45
	v_max_u32_e32 v46, v46, v45
	v_max_u32_e32 v45, v47, v52
	v_max_u32_e32 v47, v50, v51
	v_max_u32_e32 v43, v43, v44
	v_max_u32_e32 v0, v0, v42
	v_min_u32_e32 v50, v45, v47
	v_min_u32_e32 v42, v43, v0
	v_min_u32_e32 v44, v50, v42
	v_max_u32_e32 v50, v50, v42
	v_max_u32_e32 v42, v45, v47
	v_max_u32_e32 v0, v43, v0
	v_min_u32_e32 v43, v42, v0
	v_max_u32_e32 v0, v42, v0
	v_or_b32_e32 v42, s18, v5
	v_lshlrev_b32_e32 v42, 7, v42
	v_lshlrev_b32_e32 v41, 4, v41
	v_add_lshl_u32 v41, v42, v41, 2
	v_xor_b32_e32 v42, -1, v43
	v_xor_b32_e32 v0, -1, v0
	v_and_b32_e32 v43, 0x7f, v42
	v_and_b32_e32 v42, 0x7f, v0
	v_lshrrev_b32_e32 v0, 3, v42
	v_and_b32_e32 v0, 12, v0
	v_lshlrev_b32_e32 v45, 2, v42
	v_add3_u32 v0, v4, v0, v45
	v_lshrrev_b32_e32 v45, 3, v43
	v_and_b32_e32 v45, 12, v45
	v_lshlrev_b32_e32 v47, 2, v43
	v_add3_u32 v51, v4, v45, v47
	v_xor_b32_e32 v44, -1, v44
	v_xor_b32_e32 v47, -1, v50
	v_and_b32_e32 v45, 0x7f, v44
	v_and_b32_e32 v44, 0x7f, v47
	v_lshrrev_b32_e32 v47, 3, v44
	v_and_b32_e32 v47, 12, v47
	v_lshlrev_b32_e32 v50, 2, v44
	v_add3_u32 v52, v4, v47, v50
	v_lshrrev_b32_e32 v47, 3, v45
	v_xor_b32_e32 v46, -1, v46
	v_and_b32_e32 v47, 12, v47
	v_lshlrev_b32_e32 v50, 2, v45
	v_and_b32_e32 v46, 0x7f, v46
	v_add3_u32 v53, v4, v47, v50
	v_xor_b32_e32 v47, -1, v48
	v_lshrrev_b32_e32 v48, 3, v46
	v_and_b32_e32 v47, 0x7f, v47
	v_and_b32_e32 v48, 12, v48
	v_lshlrev_b32_e32 v50, 2, v46
	v_add3_u32 v54, v4, v48, v50
	v_lshrrev_b32_e32 v48, 3, v47
	v_and_b32_e32 v48, 12, v48
	v_lshlrev_b32_e32 v50, 2, v47
	v_add3_u32 v56, v4, v48, v50
	v_xor_b32_e32 v48, -1, v49
	v_xor_b32_e32 v50, -1, v55
	v_and_b32_e32 v49, 0x7f, v48
	v_and_b32_e32 v48, 0x7f, v50
	v_lshrrev_b32_e32 v50, 3, v48
	v_and_b32_e32 v50, 12, v50
	v_lshlrev_b32_e32 v55, 2, v48
	v_add3_u32 v57, v4, v50, v55
	v_lshrrev_b32_e32 v50, 3, v49
	v_and_b32_e32 v50, 12, v50
	v_lshlrev_b32_e32 v55, 2, v49
	v_add3_u32 v58, v4, v50, v55
	ds_read_b32 v50, v0 offset:34816
	ds_read_b32 v51, v51 offset:34816
	ds_read_b32 v52, v52 offset:34816
	ds_read_b32 v53, v53 offset:34816
	ds_read_b32 v54, v54 offset:34816
	ds_read_b32 v55, v56 offset:34816
	ds_read_b32 v56, v57 offset:34816
	ds_read_b32 v57, v58 offset:34816
	s_waitcnt lgkmcnt(4)
	global_store_dwordx4 v41, v[50:53], s[4:5]
	global_store_dwordx4 v41, v[42:45], s[10:11]
	v_xor_b32_e32 v0, -1, v59
	v_xor_b32_e32 v50, -1, v65
	v_xor_b32_e32 v42, -1, v66
	v_and_b32_e32 v42, 0x7f, v42
	v_and_b32_e32 v43, 0x7f, v0
	v_lshrrev_b32_e32 v0, 3, v42
	v_and_b32_e32 v0, 12, v0
	v_lshlrev_b32_e32 v44, 2, v42
	v_add3_u32 v0, v4, v0, v44
	v_lshrrev_b32_e32 v44, 3, v43
	v_and_b32_e32 v44, 12, v44
	v_lshlrev_b32_e32 v45, 2, v43
	v_add3_u32 v59, v4, v44, v45
	v_xor_b32_e32 v44, -1, v60
	v_and_b32_e32 v45, 0x7f, v44
	v_and_b32_e32 v44, 0x7f, v50
	v_lshrrev_b32_e32 v50, 3, v44
	v_and_b32_e32 v50, 12, v50
	v_lshlrev_b32_e32 v51, 2, v44
	v_add3_u32 v60, v4, v50, v51
	v_lshrrev_b32_e32 v50, 3, v45
	v_and_b32_e32 v50, 12, v50
	v_lshlrev_b32_e32 v51, 2, v45
	v_add3_u32 v62, v4, v50, v51
	v_xor_b32_e32 v50, -1, v64
	v_xor_b32_e32 v52, -1, v67
	v_and_b32_e32 v51, 0x7f, v50
	v_and_b32_e32 v50, 0x7f, v52
	v_lshrrev_b32_e32 v52, 3, v50
	v_and_b32_e32 v52, 12, v52
	v_lshlrev_b32_e32 v53, 2, v50
	v_add3_u32 v63, v4, v52, v53
	v_lshrrev_b32_e32 v52, 3, v51
	v_min_u32_e32 v68, v70, v61
	v_max_u32_e32 v61, v70, v61
	v_and_b32_e32 v52, 12, v52
	v_lshlrev_b32_e32 v53, 2, v51
	v_add3_u32 v64, v4, v52, v53
	v_xor_b32_e32 v52, -1, v68
	v_xor_b32_e32 v58, -1, v61
	v_and_b32_e32 v53, 0x7f, v52
	v_and_b32_e32 v52, 0x7f, v58
	v_lshrrev_b32_e32 v58, 3, v52
	v_and_b32_e32 v58, 12, v58
	v_lshlrev_b32_e32 v61, 2, v52
	v_add3_u32 v65, v4, v58, v61
	v_lshrrev_b32_e32 v58, 3, v53
	v_and_b32_e32 v58, 12, v58
	v_lshlrev_b32_e32 v61, 2, v53
	v_add3_u32 v66, v4, v58, v61
	ds_read_b32 v58, v0 offset:34816
	ds_read_b32 v59, v59 offset:34816
	ds_read_b32 v60, v60 offset:34816
	ds_read_b32 v61, v62 offset:34816
	ds_read_b32 v62, v63 offset:34816
	ds_read_b32 v63, v64 offset:34816
	ds_read_b32 v64, v65 offset:34816
	ds_read_b32 v65, v66 offset:34816
	s_waitcnt lgkmcnt(8)
	global_store_dwordx4 v41, v[54:57], s[4:5] offset:16
	global_store_dwordx4 v41, v[46:49], s[10:11] offset:16
	s_waitcnt lgkmcnt(4)
	global_store_dwordx4 v41, v[58:61], s[4:5] offset:32
	global_store_dwordx4 v41, v[42:45], s[10:11] offset:32
	s_waitcnt lgkmcnt(0)
	global_store_dwordx4 v41, v[62:65], s[4:5] offset:48
	global_store_dwordx4 v41, v[50:53], s[10:11] offset:48
	s_branch .LBB0_948
